# PEER output epilogue: the second round's residual rows are loaded into the first round's spent accumulators before the first round's reduce/scale/store
# speedup vs baseline: 1.0352x; 1.0352x over previous
; __device__ __forceinline__ void peer_tile(const Args& A, LAS unsigned char* lds, int tile) {
;     ...
;         for (int tk = 0; tk < 4; ++tk) {
;             const size_t m = (size_t)tile * 64 + tb + tk; const int b = (int)(m >> 11);
;             float* orow = A.out + m * 1024 + 16 * lane;
;             const float* g2 = MOD + b * 6144 + 5120 + 16 * lane;
;             f32x4 xv[4]; float ss = 0.f;
; #pragma unroll
;             for (int j = 0; j < 4; ++j) { const f32x4 x1 = *(const f32x4*)(orow + 4 * j), gg = *(const f32x4*)(g2 + 4 * j);
;                 const f32x4 pe = (f32x4){oacc[tk][2 * j][0], oacc[tk][2 * j][1], oacc[tk][2 * j + 1][0], oacc[tk][2 * j + 1][1]};
;                 xv[j] = x1 + gg * pe; ss += (xv[j][0] * xv[j][0] + xv[j][1] * xv[j][1]) + (xv[j][2] * xv[j][2] + xv[j][3] * xv[j][3]); }
;             const float rstd = rsqrtf(wave_sum(ss) * (1.f / 1024.f) + 1e-6f);
; #pragma unroll
;             for (int j = 0; j < 4; ++j) { const f32x4 fg = *(const f32x4*)(A.final_g + 16 * lane + 4 * j); *(f32x4*)(orow + 4 * j) = xv[j] * rstd * fg; }
.LV_done:
	s_waitcnt lgkmcnt(0)
	global_load_dwordx4 v[192:195], v246, s[82:83]
	global_load_dwordx4 v[196:199], v246, s[82:83] offset:16
	global_load_dwordx4 v[200:203], v246, s[82:83] offset:32
	global_load_dwordx4 v[204:207], v246, s[82:83] offset:48
	global_load_dwordx4 v[216:219], v246, s[46:47]
	global_load_dwordx4 v[220:223], v246, s[46:47] offset:16
	global_load_dwordx4 v[224:227], v246, s[46:47] offset:32
	global_load_dwordx4 v[228:231], v246, s[46:47] offset:48
	s_add_i32 s0, s77, 0
	s_lshl_b32 s0, s0, 12
	s_add_u32 s24, s48, s0
	s_addc_u32 s25, s49, 0
	s_add_i32 s0, s77, 1
	s_lshl_b32 s0, s0, 12
	s_add_u32 s26, s48, s0
	s_addc_u32 s27, s49, 0
	s_add_i32 s0, s77, 2
	s_lshl_b32 s0, s0, 12
	s_add_u32 s28, s48, s0
	s_addc_u32 s29, s49, 0
	s_add_i32 s0, s77, 3
	s_lshl_b32 s0, s0, 12
	s_add_u32 s30, s48, s0
	s_addc_u32 s31, s49, 0
	global_load_dwordx4 v[128:131], v246, s[24:25]
	global_load_dwordx4 v[132:135], v246, s[24:25] offset:16
	global_load_dwordx4 v[136:139], v246, s[24:25] offset:32
	global_load_dwordx4 v[140:143], v246, s[24:25] offset:48
	global_load_dwordx4 v[144:147], v246, s[26:27]
	global_load_dwordx4 v[148:151], v246, s[26:27] offset:16
	global_load_dwordx4 v[152:155], v246, s[26:27] offset:32
	global_load_dwordx4 v[156:159], v246, s[26:27] offset:48
	global_load_dwordx4 v[160:163], v246, s[28:29]
	global_load_dwordx4 v[164:167], v246, s[28:29] offset:16
	global_load_dwordx4 v[168:171], v246, s[28:29] offset:32
	global_load_dwordx4 v[172:175], v246, s[28:29] offset:48
	global_load_dwordx4 v[176:179], v246, s[30:31]
	global_load_dwordx4 v[180:183], v246, s[30:31] offset:16
	global_load_dwordx4 v[184:187], v246, s[30:31] offset:32
	global_load_dwordx4 v[188:191], v246, s[30:31] offset:48
	s_waitcnt vmcnt(0)
	v_pk_fma_f32 v[128:129], v[0:1], v[192:193], v[128:129]
	v_pk_fma_f32 v[130:131], v[2:3], v[194:195], v[130:131]
	v_pk_fma_f32 v[132:133], v[4:5], v[196:197], v[132:133]
	v_pk_fma_f32 v[134:135], v[6:7], v[198:199], v[134:135]
	v_pk_fma_f32 v[136:137], v[8:9], v[200:201], v[136:137]
	v_pk_fma_f32 v[138:139], v[10:11], v[202:203], v[138:139]
	v_pk_fma_f32 v[140:141], v[12:13], v[204:205], v[140:141]
	v_pk_fma_f32 v[142:143], v[14:15], v[206:207], v[142:143]
	v_pk_mul_f32 v[248:249], v[128:129], v[128:129]
	v_pk_fma_f32 v[248:249], v[130:131], v[130:131], v[248:249]
	v_pk_fma_f32 v[248:249], v[132:133], v[132:133], v[248:249]
	v_pk_fma_f32 v[248:249], v[134:135], v[134:135], v[248:249]
	v_pk_fma_f32 v[248:249], v[136:137], v[136:137], v[248:249]
	v_pk_fma_f32 v[248:249], v[138:139], v[138:139], v[248:249]
	v_pk_fma_f32 v[248:249], v[140:141], v[140:141], v[248:249]
	v_pk_fma_f32 v[248:249], v[142:143], v[142:143], v[248:249]
	v_pk_fma_f32 v[144:145], v[16:17], v[192:193], v[144:145]
	v_pk_fma_f32 v[146:147], v[18:19], v[194:195], v[146:147]
	v_pk_fma_f32 v[148:149], v[20:21], v[196:197], v[148:149]
	v_pk_fma_f32 v[150:151], v[22:23], v[198:199], v[150:151]
	v_pk_fma_f32 v[152:153], v[24:25], v[200:201], v[152:153]
	v_pk_fma_f32 v[154:155], v[26:27], v[202:203], v[154:155]
	v_pk_fma_f32 v[156:157], v[28:29], v[204:205], v[156:157]
	v_pk_fma_f32 v[158:159], v[30:31], v[206:207], v[158:159]
	v_pk_mul_f32 v[250:251], v[144:145], v[144:145]
	v_pk_fma_f32 v[250:251], v[146:147], v[146:147], v[250:251]
	v_pk_fma_f32 v[250:251], v[148:149], v[148:149], v[250:251]
	v_pk_fma_f32 v[250:251], v[150:151], v[150:151], v[250:251]
	v_pk_fma_f32 v[250:251], v[152:153], v[152:153], v[250:251]
	v_pk_fma_f32 v[250:251], v[154:155], v[154:155], v[250:251]
	v_pk_fma_f32 v[250:251], v[156:157], v[156:157], v[250:251]
	v_pk_fma_f32 v[250:251], v[158:159], v[158:159], v[250:251]
	v_pk_fma_f32 v[160:161], v[32:33], v[192:193], v[160:161]
	v_pk_fma_f32 v[162:163], v[34:35], v[194:195], v[162:163]
	v_pk_fma_f32 v[164:165], v[36:37], v[196:197], v[164:165]
	v_pk_fma_f32 v[166:167], v[38:39], v[198:199], v[166:167]
	v_pk_fma_f32 v[168:169], v[40:41], v[200:201], v[168:169]
	v_pk_fma_f32 v[170:171], v[42:43], v[202:203], v[170:171]
	v_pk_fma_f32 v[172:173], v[44:45], v[204:205], v[172:173]
	v_pk_fma_f32 v[174:175], v[46:47], v[206:207], v[174:175]
	v_pk_mul_f32 v[252:253], v[160:161], v[160:161]
	v_pk_fma_f32 v[252:253], v[162:163], v[162:163], v[252:253]
	v_pk_fma_f32 v[252:253], v[164:165], v[164:165], v[252:253]
	v_pk_fma_f32 v[252:253], v[166:167], v[166:167], v[252:253]
	v_pk_fma_f32 v[252:253], v[168:169], v[168:169], v[252:253]
	v_pk_fma_f32 v[252:253], v[170:171], v[170:171], v[252:253]
	v_pk_fma_f32 v[252:253], v[172:173], v[172:173], v[252:253]
	v_pk_fma_f32 v[252:253], v[174:175], v[174:175], v[252:253]
	v_pk_fma_f32 v[176:177], v[48:49], v[192:193], v[176:177]
	v_pk_fma_f32 v[178:179], v[50:51], v[194:195], v[178:179]
	v_pk_fma_f32 v[180:181], v[52:53], v[196:197], v[180:181]
	v_pk_fma_f32 v[182:183], v[54:55], v[198:199], v[182:183]
	v_pk_fma_f32 v[184:185], v[56:57], v[200:201], v[184:185]
	v_pk_fma_f32 v[186:187], v[58:59], v[202:203], v[186:187]
	v_pk_fma_f32 v[188:189], v[60:61], v[204:205], v[188:189]
	v_pk_fma_f32 v[190:191], v[62:63], v[206:207], v[190:191]
	v_pk_mul_f32 v[254:255], v[176:177], v[176:177]
	v_pk_fma_f32 v[254:255], v[178:179], v[178:179], v[254:255]
	v_pk_fma_f32 v[254:255], v[180:181], v[180:181], v[254:255]
	v_pk_fma_f32 v[254:255], v[182:183], v[182:183], v[254:255]
	v_pk_fma_f32 v[254:255], v[184:185], v[184:185], v[254:255]
	v_pk_fma_f32 v[254:255], v[186:187], v[186:187], v[254:255]
	v_pk_fma_f32 v[254:255], v[188:189], v[188:189], v[254:255]
	v_pk_fma_f32 v[254:255], v[190:191], v[190:191], v[254:255]
	s_add_i32 s0, s77, 4
	s_lshl_b32 s0, s0, 12
	s_add_u32 s56, s48, s0
	s_addc_u32 s57, s49, 0
; __device__ __forceinline__ void peer_tile(const Args& A, LAS unsigned char* lds, int tile) {
;     ...
;         for (int tk = 0; tk < 4; ++tk) {
;             const size_t m = (size_t)tile * 64 + tb + tk; const int b = (int)(m >> 11);
;             float* orow = A.out + m * 1024 + 16 * lane;
;             const float* g2 = MOD + b * 6144 + 5120 + 16 * lane;
;             f32x4 xv[4]; float ss = 0.f;
; #pragma unroll
;             for (int j = 0; j < 4; ++j) { const f32x4 x1 = *(const f32x4*)(orow + 4 * j), gg = *(const f32x4*)(g2 + 4 * j);
;                 const f32x4 pe = (f32x4){oacc[tk][2 * j][0], oacc[tk][2 * j][1], oacc[tk][2 * j + 1][0], oacc[tk][2 * j + 1][1]};
;                 xv[j] = x1 + gg * pe; ss += (xv[j][0] * xv[j][0] + xv[j][1] * xv[j][1]) + (xv[j][2] * xv[j][2] + xv[j][3] * xv[j][3]); }
;             const float rstd = rsqrtf(wave_sum(ss) * (1.f / 1024.f) + 1e-6f);
; #pragma unroll
;             for (int j = 0; j < 4; ++j) { const f32x4 fg = *(const f32x4*)(A.final_g + 16 * lane + 4 * j); *(f32x4*)(orow + 4 * j) = xv[j] * rstd * fg; }
	s_add_i32 s0, s77, 5
	s_lshl_b32 s0, s0, 12
	s_add_u32 s58, s48, s0
	s_addc_u32 s59, s49, 0
	s_add_i32 s0, s77, 6
	s_lshl_b32 s0, s0, 12
	s_add_u32 s60, s48, s0
	s_addc_u32 s61, s49, 0
	s_add_i32 s0, s77, 7
	s_lshl_b32 s0, s0, 12
	s_add_u32 s62, s48, s0
	s_addc_u32 s63, s49, 0
	global_load_dwordx4 v[0:3], v246, s[56:57]
	global_load_dwordx4 v[4:7], v246, s[56:57] offset:16
	global_load_dwordx4 v[8:11], v246, s[56:57] offset:32
	global_load_dwordx4 v[12:15], v246, s[56:57] offset:48
	global_load_dwordx4 v[16:19], v246, s[58:59]
	global_load_dwordx4 v[20:23], v246, s[58:59] offset:16
	global_load_dwordx4 v[24:27], v246, s[58:59] offset:32
	global_load_dwordx4 v[28:31], v246, s[58:59] offset:48
	global_load_dwordx4 v[32:35], v246, s[60:61]
	global_load_dwordx4 v[36:39], v246, s[60:61] offset:16
	global_load_dwordx4 v[40:43], v246, s[60:61] offset:32
	global_load_dwordx4 v[44:47], v246, s[60:61] offset:48
	global_load_dwordx4 v[48:51], v246, s[62:63]
	global_load_dwordx4 v[52:55], v246, s[62:63] offset:16
	global_load_dwordx4 v[56:59], v246, s[62:63] offset:32
	global_load_dwordx4 v[60:63], v246, s[62:63] offset:48
	v_add_f32_e32 v248, v248, v249
	v_add_f32_e32 v250, v250, v251
	v_add_f32_e32 v252, v252, v253
	v_add_f32_e32 v254, v254, v255
	v_mov_b32_e32 v249, v248
	v_mov_b32_e32 v251, v250
	v_mov_b32_e32 v253, v252
	v_mov_b32_e32 v255, v254
	v_permlane32_swap_b32_e32 v248, v249
	v_permlane32_swap_b32_e32 v250, v251
	v_permlane32_swap_b32_e32 v252, v253
	v_permlane32_swap_b32_e32 v254, v255
	v_add_f32_e32 v248, v248, v249
	v_add_f32_e32 v250, v250, v251
	v_add_f32_e32 v252, v252, v253
	v_add_f32_e32 v254, v254, v255
	v_mov_b32_e32 v249, v248
	v_mov_b32_e32 v251, v250
	v_mov_b32_e32 v253, v252
	v_mov_b32_e32 v255, v254
	v_permlane16_swap_b32_e32 v248, v249
	v_permlane16_swap_b32_e32 v250, v251
	v_permlane16_swap_b32_e32 v252, v253
	v_permlane16_swap_b32_e32 v254, v255
	v_add_f32_e32 v248, v248, v249
	v_add_f32_e32 v250, v250, v251
	v_add_f32_e32 v252, v252, v253
	v_add_f32_e32 v254, v254, v255
	v_add_f32_dpp v248, v248, v248 quad_perm:[1,0,3,2] row_mask:0xf bank_mask:0xf bound_ctrl:1
	v_add_f32_dpp v250, v250, v250 quad_perm:[1,0,3,2] row_mask:0xf bank_mask:0xf bound_ctrl:1
	v_add_f32_dpp v252, v252, v252 quad_perm:[1,0,3,2] row_mask:0xf bank_mask:0xf bound_ctrl:1
	v_add_f32_dpp v254, v254, v254 quad_perm:[1,0,3,2] row_mask:0xf bank_mask:0xf bound_ctrl:1
	v_add_f32_dpp v248, v248, v248 quad_perm:[2,3,0,1] row_mask:0xf bank_mask:0xf bound_ctrl:1
	v_add_f32_dpp v250, v250, v250 quad_perm:[2,3,0,1] row_mask:0xf bank_mask:0xf bound_ctrl:1
	v_add_f32_dpp v252, v252, v252 quad_perm:[2,3,0,1] row_mask:0xf bank_mask:0xf bound_ctrl:1
	v_add_f32_dpp v254, v254, v254 quad_perm:[2,3,0,1] row_mask:0xf bank_mask:0xf bound_ctrl:1
	v_add_f32_dpp v248, v248, v248 row_half_mirror row_mask:0xf bank_mask:0xf bound_ctrl:1
	v_add_f32_dpp v250, v250, v250 row_half_mirror row_mask:0xf bank_mask:0xf bound_ctrl:1
	v_add_f32_dpp v252, v252, v252 row_half_mirror row_mask:0xf bank_mask:0xf bound_ctrl:1
	v_add_f32_dpp v254, v254, v254 row_half_mirror row_mask:0xf bank_mask:0xf bound_ctrl:1
	v_add_f32_dpp v248, v248, v248 row_mirror row_mask:0xf bank_mask:0xf bound_ctrl:1
	v_add_f32_dpp v250, v250, v250 row_mirror row_mask:0xf bank_mask:0xf bound_ctrl:1
	v_add_f32_dpp v252, v252, v252 row_mirror row_mask:0xf bank_mask:0xf bound_ctrl:1
	v_add_f32_dpp v254, v254, v254 row_mirror row_mask:0xf bank_mask:0xf bound_ctrl:1
	v_fmamk_f32 v248, v248, 0x3a800000, v243
	v_fmamk_f32 v250, v250, 0x3a800000, v243
	v_fmamk_f32 v252, v252, 0x3a800000, v243
	v_fmamk_f32 v254, v254, 0x3a800000, v243
	v_rsq_f32_e32 v248, v248
	v_rsq_f32_e32 v250, v250
	v_rsq_f32_e32 v252, v252
	v_rsq_f32_e32 v254, v254
	s_nop 0
	v_pk_mul_f32 v[128:129], v[128:129], v[248:249] op_sel_hi:[1,0]
	v_pk_mul_f32 v[130:131], v[130:131], v[248:249] op_sel_hi:[1,0]
	v_pk_mul_f32 v[132:133], v[132:133], v[248:249] op_sel_hi:[1,0]
	v_pk_mul_f32 v[134:135], v[134:135], v[248:249] op_sel_hi:[1,0]
	v_pk_mul_f32 v[136:137], v[136:137], v[248:249] op_sel_hi:[1,0]
	v_pk_mul_f32 v[138:139], v[138:139], v[248:249] op_sel_hi:[1,0]
	v_pk_mul_f32 v[140:141], v[140:141], v[248:249] op_sel_hi:[1,0]
	v_pk_mul_f32 v[142:143], v[142:143], v[248:249] op_sel_hi:[1,0]
	v_pk_mul_f32 v[128:129], v[216:217], v[128:129]
	v_pk_mul_f32 v[130:131], v[218:219], v[130:131]
	v_pk_mul_f32 v[132:133], v[220:221], v[132:133]
	v_pk_mul_f32 v[134:135], v[222:223], v[134:135]
	v_pk_mul_f32 v[136:137], v[224:225], v[136:137]
	v_pk_mul_f32 v[138:139], v[226:227], v[138:139]
	v_pk_mul_f32 v[140:141], v[228:229], v[140:141]
	v_pk_mul_f32 v[142:143], v[230:231], v[142:143]
	global_store_dwordx4 v246, v[128:131], s[24:25]
	global_store_dwordx4 v246, v[132:135], s[24:25] offset:16
	global_store_dwordx4 v246, v[136:139], s[24:25] offset:32
	global_store_dwordx4 v246, v[140:143], s[24:25] offset:48
	v_pk_mul_f32 v[144:145], v[144:145], v[250:251] op_sel_hi:[1,0]
	v_pk_mul_f32 v[146:147], v[146:147], v[250:251] op_sel_hi:[1,0]
	v_pk_mul_f32 v[148:149], v[148:149], v[250:251] op_sel_hi:[1,0]
	v_pk_mul_f32 v[150:151], v[150:151], v[250:251] op_sel_hi:[1,0]
	v_pk_mul_f32 v[152:153], v[152:153], v[250:251] op_sel_hi:[1,0]
	v_pk_mul_f32 v[154:155], v[154:155], v[250:251] op_sel_hi:[1,0]
	v_pk_mul_f32 v[156:157], v[156:157], v[250:251] op_sel_hi:[1,0]
	v_pk_mul_f32 v[158:159], v[158:159], v[250:251] op_sel_hi:[1,0]
	v_pk_mul_f32 v[144:145], v[216:217], v[144:145]
	v_pk_mul_f32 v[146:147], v[218:219], v[146:147]
	v_pk_mul_f32 v[148:149], v[220:221], v[148:149]
	v_pk_mul_f32 v[150:151], v[222:223], v[150:151]
	v_pk_mul_f32 v[152:153], v[224:225], v[152:153]
; __device__ __forceinline__ void peer_tile(const Args& A, LAS unsigned char* lds, int tile) {
;     ...
;         for (int tk = 0; tk < 4; ++tk) {
;             const size_t m = (size_t)tile * 64 + tb + tk; const int b = (int)(m >> 11);
;             float* orow = A.out + m * 1024 + 16 * lane;
;             const float* g2 = MOD + b * 6144 + 5120 + 16 * lane;
;             f32x4 xv[4]; float ss = 0.f;
; #pragma unroll
;             for (int j = 0; j < 4; ++j) { const f32x4 x1 = *(const f32x4*)(orow + 4 * j), gg = *(const f32x4*)(g2 + 4 * j);
;                 const f32x4 pe = (f32x4){oacc[tk][2 * j][0], oacc[tk][2 * j][1], oacc[tk][2 * j + 1][0], oacc[tk][2 * j + 1][1]};
;                 xv[j] = x1 + gg * pe; ss += (xv[j][0] * xv[j][0] + xv[j][1] * xv[j][1]) + (xv[j][2] * xv[j][2] + xv[j][3] * xv[j][3]); }
;             const float rstd = rsqrtf(wave_sum(ss) * (1.f / 1024.f) + 1e-6f);
; #pragma unroll
;             for (int j = 0; j < 4; ++j) { const f32x4 fg = *(const f32x4*)(A.final_g + 16 * lane + 4 * j); *(f32x4*)(orow + 4 * j) = xv[j] * rstd * fg; }
	v_pk_mul_f32 v[154:155], v[226:227], v[154:155]
	v_pk_mul_f32 v[156:157], v[228:229], v[156:157]
	v_pk_mul_f32 v[158:159], v[230:231], v[158:159]
	global_store_dwordx4 v246, v[144:147], s[26:27]
	global_store_dwordx4 v246, v[148:151], s[26:27] offset:16
	global_store_dwordx4 v246, v[152:155], s[26:27] offset:32
	global_store_dwordx4 v246, v[156:159], s[26:27] offset:48
	v_pk_mul_f32 v[160:161], v[160:161], v[252:253] op_sel_hi:[1,0]
	v_pk_mul_f32 v[162:163], v[162:163], v[252:253] op_sel_hi:[1,0]
	v_pk_mul_f32 v[164:165], v[164:165], v[252:253] op_sel_hi:[1,0]
	v_pk_mul_f32 v[166:167], v[166:167], v[252:253] op_sel_hi:[1,0]
	v_pk_mul_f32 v[168:169], v[168:169], v[252:253] op_sel_hi:[1,0]
	v_pk_mul_f32 v[170:171], v[170:171], v[252:253] op_sel_hi:[1,0]
	v_pk_mul_f32 v[172:173], v[172:173], v[252:253] op_sel_hi:[1,0]
	v_pk_mul_f32 v[174:175], v[174:175], v[252:253] op_sel_hi:[1,0]
	v_pk_mul_f32 v[160:161], v[216:217], v[160:161]
	v_pk_mul_f32 v[162:163], v[218:219], v[162:163]
	v_pk_mul_f32 v[164:165], v[220:221], v[164:165]
	v_pk_mul_f32 v[166:167], v[222:223], v[166:167]
	v_pk_mul_f32 v[168:169], v[224:225], v[168:169]
	v_pk_mul_f32 v[170:171], v[226:227], v[170:171]
	v_pk_mul_f32 v[172:173], v[228:229], v[172:173]
	v_pk_mul_f32 v[174:175], v[230:231], v[174:175]
	global_store_dwordx4 v246, v[160:163], s[28:29]
	global_store_dwordx4 v246, v[164:167], s[28:29] offset:16
	global_store_dwordx4 v246, v[168:171], s[28:29] offset:32
	global_store_dwordx4 v246, v[172:175], s[28:29] offset:48
	v_pk_mul_f32 v[176:177], v[176:177], v[254:255] op_sel_hi:[1,0]
	v_pk_mul_f32 v[178:179], v[178:179], v[254:255] op_sel_hi:[1,0]
	v_pk_mul_f32 v[180:181], v[180:181], v[254:255] op_sel_hi:[1,0]
	v_pk_mul_f32 v[182:183], v[182:183], v[254:255] op_sel_hi:[1,0]
	v_pk_mul_f32 v[184:185], v[184:185], v[254:255] op_sel_hi:[1,0]
	v_pk_mul_f32 v[186:187], v[186:187], v[254:255] op_sel_hi:[1,0]
	v_pk_mul_f32 v[188:189], v[188:189], v[254:255] op_sel_hi:[1,0]
	v_pk_mul_f32 v[190:191], v[190:191], v[254:255] op_sel_hi:[1,0]
	v_pk_mul_f32 v[176:177], v[216:217], v[176:177]
	v_pk_mul_f32 v[178:179], v[218:219], v[178:179]
	v_pk_mul_f32 v[180:181], v[220:221], v[180:181]
	v_pk_mul_f32 v[182:183], v[222:223], v[182:183]
	v_pk_mul_f32 v[184:185], v[224:225], v[184:185]
	v_pk_mul_f32 v[186:187], v[226:227], v[186:187]
	v_pk_mul_f32 v[188:189], v[228:229], v[188:189]
	v_pk_mul_f32 v[190:191], v[230:231], v[190:191]
	global_store_dwordx4 v246, v[176:179], s[30:31]
	global_store_dwordx4 v246, v[180:183], s[30:31] offset:16
	global_store_dwordx4 v246, v[184:187], s[30:31] offset:32
	global_store_dwordx4 v246, v[188:191], s[30:31] offset:48
	s_nop 1
	s_waitcnt vmcnt(16)
	v_pk_fma_f32 v[0:1], v[64:65], v[192:193], v[0:1]
	v_pk_fma_f32 v[2:3], v[66:67], v[194:195], v[2:3]
	v_pk_fma_f32 v[4:5], v[68:69], v[196:197], v[4:5]
	v_pk_fma_f32 v[6:7], v[70:71], v[198:199], v[6:7]
	v_pk_fma_f32 v[8:9], v[72:73], v[200:201], v[8:9]
	v_pk_fma_f32 v[10:11], v[74:75], v[202:203], v[10:11]
	v_pk_fma_f32 v[12:13], v[76:77], v[204:205], v[12:13]
	v_pk_fma_f32 v[14:15], v[78:79], v[206:207], v[14:15]
	v_pk_mul_f32 v[248:249], v[0:1], v[0:1]
	v_pk_fma_f32 v[248:249], v[2:3], v[2:3], v[248:249]
	v_pk_fma_f32 v[248:249], v[4:5], v[4:5], v[248:249]
	v_pk_fma_f32 v[248:249], v[6:7], v[6:7], v[248:249]
	v_pk_fma_f32 v[248:249], v[8:9], v[8:9], v[248:249]
	v_pk_fma_f32 v[248:249], v[10:11], v[10:11], v[248:249]
	v_pk_fma_f32 v[248:249], v[12:13], v[12:13], v[248:249]
	v_pk_fma_f32 v[248:249], v[14:15], v[14:15], v[248:249]
	v_pk_fma_f32 v[16:17], v[80:81], v[192:193], v[16:17]
	v_pk_fma_f32 v[18:19], v[82:83], v[194:195], v[18:19]
	v_pk_fma_f32 v[20:21], v[84:85], v[196:197], v[20:21]
	v_pk_fma_f32 v[22:23], v[86:87], v[198:199], v[22:23]
	v_pk_fma_f32 v[24:25], v[88:89], v[200:201], v[24:25]
	v_pk_fma_f32 v[26:27], v[90:91], v[202:203], v[26:27]
	v_pk_fma_f32 v[28:29], v[92:93], v[204:205], v[28:29]
	v_pk_fma_f32 v[30:31], v[94:95], v[206:207], v[30:31]
	v_pk_mul_f32 v[250:251], v[16:17], v[16:17]
	v_pk_fma_f32 v[250:251], v[18:19], v[18:19], v[250:251]
	v_pk_fma_f32 v[250:251], v[20:21], v[20:21], v[250:251]
	v_pk_fma_f32 v[250:251], v[22:23], v[22:23], v[250:251]
	v_pk_fma_f32 v[250:251], v[24:25], v[24:25], v[250:251]
	v_pk_fma_f32 v[250:251], v[26:27], v[26:27], v[250:251]
	v_pk_fma_f32 v[250:251], v[28:29], v[28:29], v[250:251]
	v_pk_fma_f32 v[250:251], v[30:31], v[30:31], v[250:251]
	v_pk_fma_f32 v[32:33], v[96:97], v[192:193], v[32:33]
	v_pk_fma_f32 v[34:35], v[98:99], v[194:195], v[34:35]
	v_pk_fma_f32 v[36:37], v[100:101], v[196:197], v[36:37]
	v_pk_fma_f32 v[38:39], v[102:103], v[198:199], v[38:39]
	v_pk_fma_f32 v[40:41], v[104:105], v[200:201], v[40:41]
	v_pk_fma_f32 v[42:43], v[106:107], v[202:203], v[42:43]
	v_pk_fma_f32 v[44:45], v[108:109], v[204:205], v[44:45]
	v_pk_fma_f32 v[46:47], v[110:111], v[206:207], v[46:47]
	v_pk_mul_f32 v[252:253], v[32:33], v[32:33]
	v_pk_fma_f32 v[252:253], v[34:35], v[34:35], v[252:253]
	v_pk_fma_f32 v[252:253], v[36:37], v[36:37], v[252:253]
	v_pk_fma_f32 v[252:253], v[38:39], v[38:39], v[252:253]
	v_pk_fma_f32 v[252:253], v[40:41], v[40:41], v[252:253]
	v_pk_fma_f32 v[252:253], v[42:43], v[42:43], v[252:253]
	v_pk_fma_f32 v[252:253], v[44:45], v[44:45], v[252:253]
	v_pk_fma_f32 v[252:253], v[46:47], v[46:47], v[252:253]
	v_pk_fma_f32 v[48:49], v[112:113], v[192:193], v[48:49]
	v_pk_fma_f32 v[50:51], v[114:115], v[194:195], v[50:51]
	v_pk_fma_f32 v[52:53], v[116:117], v[196:197], v[52:53]
	v_pk_fma_f32 v[54:55], v[118:119], v[198:199], v[54:55]
	v_pk_fma_f32 v[56:57], v[120:121], v[200:201], v[56:57]
	v_pk_fma_f32 v[58:59], v[122:123], v[202:203], v[58:59]
; __device__ __forceinline__ void peer_tile(const Args& A, LAS unsigned char* lds, int tile) {
;     ...
;         for (int tk = 0; tk < 4; ++tk) {
;             const size_t m = (size_t)tile * 64 + tb + tk; const int b = (int)(m >> 11);
;             float* orow = A.out + m * 1024 + 16 * lane;
;             const float* g2 = MOD + b * 6144 + 5120 + 16 * lane;
;             f32x4 xv[4]; float ss = 0.f;
; #pragma unroll
;             for (int j = 0; j < 4; ++j) { const f32x4 x1 = *(const f32x4*)(orow + 4 * j), gg = *(const f32x4*)(g2 + 4 * j);
;                 const f32x4 pe = (f32x4){oacc[tk][2 * j][0], oacc[tk][2 * j][1], oacc[tk][2 * j + 1][0], oacc[tk][2 * j + 1][1]};
;                 xv[j] = x1 + gg * pe; ss += (xv[j][0] * xv[j][0] + xv[j][1] * xv[j][1]) + (xv[j][2] * xv[j][2] + xv[j][3] * xv[j][3]); }
;             const float rstd = rsqrtf(wave_sum(ss) * (1.f / 1024.f) + 1e-6f);
; #pragma unroll
;             for (int j = 0; j < 4; ++j) { const f32x4 fg = *(const f32x4*)(A.final_g + 16 * lane + 4 * j); *(f32x4*)(orow + 4 * j) = xv[j] * rstd * fg; }
	v_pk_fma_f32 v[60:61], v[124:125], v[204:205], v[60:61]
	v_pk_fma_f32 v[62:63], v[126:127], v[206:207], v[62:63]
	v_pk_mul_f32 v[254:255], v[48:49], v[48:49]
	v_pk_fma_f32 v[254:255], v[50:51], v[50:51], v[254:255]
	v_pk_fma_f32 v[254:255], v[52:53], v[52:53], v[254:255]
	v_pk_fma_f32 v[254:255], v[54:55], v[54:55], v[254:255]
	v_pk_fma_f32 v[254:255], v[56:57], v[56:57], v[254:255]
	v_pk_fma_f32 v[254:255], v[58:59], v[58:59], v[254:255]
	v_pk_fma_f32 v[254:255], v[60:61], v[60:61], v[254:255]
	v_pk_fma_f32 v[254:255], v[62:63], v[62:63], v[254:255]
	v_add_f32_e32 v248, v248, v249
	v_add_f32_e32 v250, v250, v251
	v_add_f32_e32 v252, v252, v253
	v_add_f32_e32 v254, v254, v255
	v_mov_b32_e32 v249, v248
	v_mov_b32_e32 v251, v250
	v_mov_b32_e32 v253, v252
	v_mov_b32_e32 v255, v254
	v_permlane32_swap_b32_e32 v248, v249
	v_permlane32_swap_b32_e32 v250, v251
	v_permlane32_swap_b32_e32 v252, v253
	v_permlane32_swap_b32_e32 v254, v255
	v_add_f32_e32 v248, v248, v249
	v_add_f32_e32 v250, v250, v251
	v_add_f32_e32 v252, v252, v253
	v_add_f32_e32 v254, v254, v255
	v_mov_b32_e32 v249, v248
	v_mov_b32_e32 v251, v250
	v_mov_b32_e32 v253, v252
	v_mov_b32_e32 v255, v254
	v_permlane16_swap_b32_e32 v248, v249
	v_permlane16_swap_b32_e32 v250, v251
	v_permlane16_swap_b32_e32 v252, v253
	v_permlane16_swap_b32_e32 v254, v255
	v_add_f32_e32 v248, v248, v249
	v_add_f32_e32 v250, v250, v251
	v_add_f32_e32 v252, v252, v253
	v_add_f32_e32 v254, v254, v255
	v_add_f32_dpp v248, v248, v248 quad_perm:[1,0,3,2] row_mask:0xf bank_mask:0xf bound_ctrl:1
	v_add_f32_dpp v250, v250, v250 quad_perm:[1,0,3,2] row_mask:0xf bank_mask:0xf bound_ctrl:1
	v_add_f32_dpp v252, v252, v252 quad_perm:[1,0,3,2] row_mask:0xf bank_mask:0xf bound_ctrl:1
	v_add_f32_dpp v254, v254, v254 quad_perm:[1,0,3,2] row_mask:0xf bank_mask:0xf bound_ctrl:1
	v_add_f32_dpp v248, v248, v248 quad_perm:[2,3,0,1] row_mask:0xf bank_mask:0xf bound_ctrl:1
	v_add_f32_dpp v250, v250, v250 quad_perm:[2,3,0,1] row_mask:0xf bank_mask:0xf bound_ctrl:1
	v_add_f32_dpp v252, v252, v252 quad_perm:[2,3,0,1] row_mask:0xf bank_mask:0xf bound_ctrl:1
	v_add_f32_dpp v254, v254, v254 quad_perm:[2,3,0,1] row_mask:0xf bank_mask:0xf bound_ctrl:1
	v_add_f32_dpp v248, v248, v248 row_half_mirror row_mask:0xf bank_mask:0xf bound_ctrl:1
	v_add_f32_dpp v250, v250, v250 row_half_mirror row_mask:0xf bank_mask:0xf bound_ctrl:1
	v_add_f32_dpp v252, v252, v252 row_half_mirror row_mask:0xf bank_mask:0xf bound_ctrl:1
	v_add_f32_dpp v254, v254, v254 row_half_mirror row_mask:0xf bank_mask:0xf bound_ctrl:1
	v_add_f32_dpp v248, v248, v248 row_mirror row_mask:0xf bank_mask:0xf bound_ctrl:1
	v_add_f32_dpp v250, v250, v250 row_mirror row_mask:0xf bank_mask:0xf bound_ctrl:1
	v_add_f32_dpp v252, v252, v252 row_mirror row_mask:0xf bank_mask:0xf bound_ctrl:1
	v_add_f32_dpp v254, v254, v254 row_mirror row_mask:0xf bank_mask:0xf bound_ctrl:1
	v_fmamk_f32 v248, v248, 0x3a800000, v243
	v_fmamk_f32 v250, v250, 0x3a800000, v243
	v_fmamk_f32 v252, v252, 0x3a800000, v243
	v_fmamk_f32 v254, v254, 0x3a800000, v243
	v_rsq_f32_e32 v248, v248
	v_rsq_f32_e32 v250, v250
	v_rsq_f32_e32 v252, v252
	v_rsq_f32_e32 v254, v254
	s_nop 0
	v_pk_mul_f32 v[0:1], v[0:1], v[248:249] op_sel_hi:[1,0]
	v_pk_mul_f32 v[2:3], v[2:3], v[248:249] op_sel_hi:[1,0]
	v_pk_mul_f32 v[4:5], v[4:5], v[248:249] op_sel_hi:[1,0]
	v_pk_mul_f32 v[6:7], v[6:7], v[248:249] op_sel_hi:[1,0]
	v_pk_mul_f32 v[8:9], v[8:9], v[248:249] op_sel_hi:[1,0]
	v_pk_mul_f32 v[10:11], v[10:11], v[248:249] op_sel_hi:[1,0]
	v_pk_mul_f32 v[12:13], v[12:13], v[248:249] op_sel_hi:[1,0]
	v_pk_mul_f32 v[14:15], v[14:15], v[248:249] op_sel_hi:[1,0]
	v_pk_mul_f32 v[0:1], v[216:217], v[0:1]
	v_pk_mul_f32 v[2:3], v[218:219], v[2:3]
	v_pk_mul_f32 v[4:5], v[220:221], v[4:5]
	v_pk_mul_f32 v[6:7], v[222:223], v[6:7]
; __device__ __forceinline__ void peer_tile(const Args& A, LAS unsigned char* lds, int tile) {
;     ...
;         for (int tk = 0; tk < 4; ++tk) {
;             const size_t m = (size_t)tile * 64 + tb + tk; const int b = (int)(m >> 11);
;             float* orow = A.out + m * 1024 + 16 * lane;
;             const float* g2 = MOD + b * 6144 + 5120 + 16 * lane;
;             f32x4 xv[4]; float ss = 0.f;
; #pragma unroll
;             for (int j = 0; j < 4; ++j) { const f32x4 x1 = *(const f32x4*)(orow + 4 * j), gg = *(const f32x4*)(g2 + 4 * j);
;                 const f32x4 pe = (f32x4){oacc[tk][2 * j][0], oacc[tk][2 * j][1], oacc[tk][2 * j + 1][0], oacc[tk][2 * j + 1][1]};
;                 xv[j] = x1 + gg * pe; ss += (xv[j][0] * xv[j][0] + xv[j][1] * xv[j][1]) + (xv[j][2] * xv[j][2] + xv[j][3] * xv[j][3]); }
;             const float rstd = rsqrtf(wave_sum(ss) * (1.f / 1024.f) + 1e-6f);
; #pragma unroll
;             for (int j = 0; j < 4; ++j) { const f32x4 fg = *(const f32x4*)(A.final_g + 16 * lane + 4 * j); *(f32x4*)(orow + 4 * j) = xv[j] * rstd * fg; }
	v_pk_mul_f32 v[8:9], v[224:225], v[8:9]
	v_pk_mul_f32 v[10:11], v[226:227], v[10:11]
	v_pk_mul_f32 v[12:13], v[228:229], v[12:13]
	v_pk_mul_f32 v[14:15], v[230:231], v[14:15]
	global_store_dwordx4 v246, v[0:3], s[56:57]
	global_store_dwordx4 v246, v[4:7], s[56:57] offset:16
	global_store_dwordx4 v246, v[8:11], s[56:57] offset:32
	global_store_dwordx4 v246, v[12:15], s[56:57] offset:48
	v_pk_mul_f32 v[16:17], v[16:17], v[250:251] op_sel_hi:[1,0]
	v_pk_mul_f32 v[18:19], v[18:19], v[250:251] op_sel_hi:[1,0]
	v_pk_mul_f32 v[20:21], v[20:21], v[250:251] op_sel_hi:[1,0]
	v_pk_mul_f32 v[22:23], v[22:23], v[250:251] op_sel_hi:[1,0]
	v_pk_mul_f32 v[24:25], v[24:25], v[250:251] op_sel_hi:[1,0]
	v_pk_mul_f32 v[26:27], v[26:27], v[250:251] op_sel_hi:[1,0]
	v_pk_mul_f32 v[28:29], v[28:29], v[250:251] op_sel_hi:[1,0]
	v_pk_mul_f32 v[30:31], v[30:31], v[250:251] op_sel_hi:[1,0]
	v_pk_mul_f32 v[16:17], v[216:217], v[16:17]
	v_pk_mul_f32 v[18:19], v[218:219], v[18:19]
	v_pk_mul_f32 v[20:21], v[220:221], v[20:21]
	v_pk_mul_f32 v[22:23], v[222:223], v[22:23]
	v_pk_mul_f32 v[24:25], v[224:225], v[24:25]
	v_pk_mul_f32 v[26:27], v[226:227], v[26:27]
	v_pk_mul_f32 v[28:29], v[228:229], v[28:29]
	v_pk_mul_f32 v[30:31], v[230:231], v[30:31]
	global_store_dwordx4 v246, v[16:19], s[58:59]
	global_store_dwordx4 v246, v[20:23], s[58:59] offset:16
	global_store_dwordx4 v246, v[24:27], s[58:59] offset:32
	global_store_dwordx4 v246, v[28:31], s[58:59] offset:48
	v_pk_mul_f32 v[32:33], v[32:33], v[252:253] op_sel_hi:[1,0]
	v_pk_mul_f32 v[34:35], v[34:35], v[252:253] op_sel_hi:[1,0]
	v_pk_mul_f32 v[36:37], v[36:37], v[252:253] op_sel_hi:[1,0]
	v_pk_mul_f32 v[38:39], v[38:39], v[252:253] op_sel_hi:[1,0]
	v_pk_mul_f32 v[40:41], v[40:41], v[252:253] op_sel_hi:[1,0]
	v_pk_mul_f32 v[42:43], v[42:43], v[252:253] op_sel_hi:[1,0]
	v_pk_mul_f32 v[44:45], v[44:45], v[252:253] op_sel_hi:[1,0]
	v_pk_mul_f32 v[46:47], v[46:47], v[252:253] op_sel_hi:[1,0]
	v_pk_mul_f32 v[32:33], v[216:217], v[32:33]
	v_pk_mul_f32 v[34:35], v[218:219], v[34:35]
	v_pk_mul_f32 v[36:37], v[220:221], v[36:37]
	v_pk_mul_f32 v[38:39], v[222:223], v[38:39]
	v_pk_mul_f32 v[40:41], v[224:225], v[40:41]
	v_pk_mul_f32 v[42:43], v[226:227], v[42:43]
	v_pk_mul_f32 v[44:45], v[228:229], v[44:45]
	v_pk_mul_f32 v[46:47], v[230:231], v[46:47]
	global_store_dwordx4 v246, v[32:35], s[60:61]
	global_store_dwordx4 v246, v[36:39], s[60:61] offset:16
	global_store_dwordx4 v246, v[40:43], s[60:61] offset:32
	global_store_dwordx4 v246, v[44:47], s[60:61] offset:48
	v_pk_mul_f32 v[48:49], v[48:49], v[254:255] op_sel_hi:[1,0]
	v_pk_mul_f32 v[50:51], v[50:51], v[254:255] op_sel_hi:[1,0]
	v_pk_mul_f32 v[52:53], v[52:53], v[254:255] op_sel_hi:[1,0]
	v_pk_mul_f32 v[54:55], v[54:55], v[254:255] op_sel_hi:[1,0]
	v_pk_mul_f32 v[56:57], v[56:57], v[254:255] op_sel_hi:[1,0]
	v_pk_mul_f32 v[58:59], v[58:59], v[254:255] op_sel_hi:[1,0]
	v_pk_mul_f32 v[60:61], v[60:61], v[254:255] op_sel_hi:[1,0]
	v_pk_mul_f32 v[62:63], v[62:63], v[254:255] op_sel_hi:[1,0]
	v_pk_mul_f32 v[48:49], v[216:217], v[48:49]
	v_pk_mul_f32 v[50:51], v[218:219], v[50:51]
	v_pk_mul_f32 v[52:53], v[220:221], v[52:53]
	v_pk_mul_f32 v[54:55], v[222:223], v[54:55]
	v_pk_mul_f32 v[56:57], v[224:225], v[56:57]
	v_pk_mul_f32 v[58:59], v[226:227], v[58:59]
	v_pk_mul_f32 v[60:61], v[228:229], v[60:61]
	v_pk_mul_f32 v[62:63], v[230:231], v[62:63]
	global_store_dwordx4 v246, v[48:51], s[62:63]
	global_store_dwordx4 v246, v[52:55], s[62:63] offset:16
	global_store_dwordx4 v246, v[56:59], s[62:63] offset:32
	global_store_dwordx4 v246, v[60:63], s[62:63] offset:48
	s_nop 1
	v_mov_b32_e32 v113, 0
	v_mbcnt_lo_u32_b32 v215, -1, 0
	v_mbcnt_hi_u32_b32 v215, -1, v215
	v_and_b32_e32 v216, 64, v215
	v_add_u32_e32 v216, 64, v216
	v_xor_b32_e32 v217, 16, v215
	v_xor_b32_e32 v218, 32, v215
	s_branch .LBB0_698

